# attention QK block: K-fragment read ring keeps six fragments in flight through the last key blocks (four extra register groups v234-v249, restored at loop exit for the last-tile code)
# speedup vs baseline: 1.0048x; 1.0048x over previous
.LBB0_999:
	s_add_i32 s28, s29, 1
	s_cmp_lt_u32 s29, 3
	s_cselect_b32 s8, s27, s13
	s_ashr_i32 s9, s8, 31
	s_mul_i32 s10, s8, 0xc00
	s_mul_hi_i32 s11, s8, 0xc00
	s_add_u32 s10, s16, s10
	s_addc_u32 s11, s17, s11
	s_lshl_b64 s[8:9], s[8:9], 1
	s_add_u32 vcc_lo, s18, s8
	s_addc_u32 vcc_hi, s19, s9
	s_bitcmp1_b32 s28, 0
	s_cselect_b32 s12, 0xa800, 0
	v_readfirstlane_b32 s30, v181
	s_add_i32 s30, s30, s12
	s_bitcmp1_b32 s29, 0
	s_cselect_b32 s8, 0xa800, 0
	v_add_u32_e32 v159, s8, v198
	v_add_u32_e32 v173, s8, v199
	v_add_u32_e32 v175, s8, v200
	v_add_u32_e32 v177, s8, v201
	v_add_u32_e32 v179, s8, v225
	v_add_u32_e32 v195, s8, v226
	ds_read_b128 v[116:119], v159
	ds_read_b128 v[124:127], v173
	ds_read_b128 v[128:131], v175
	ds_read_b128 v[136:139], v177
	ds_read_b128 v[132:135], v179
	ds_read_b128 v[140:143], v195
	s_waitcnt lgkmcnt(5)
	v_mfma_f32_16x16x32_bf16 v[112:115], v[116:119], v[104:107], 0
	v_mfma_f32_16x16x32_bf16 v[120:123], v[116:119], v[108:111], 0
	ds_read_b128 v[204:207], v159 offset:6144
	s_waitcnt lgkmcnt(5)
	v_mfma_f32_16x16x32_bf16 v[112:115], v[124:127], v[96:99], v[112:115]
	v_mfma_f32_16x16x32_bf16 v[120:123], v[124:127], v[100:103], v[120:123]
	ds_read_b128 v[208:211], v173 offset:6144
	s_add_i32 m0, s30, 0x0
	s_waitcnt lgkmcnt(5)
	v_mfma_f32_16x16x32_bf16 v[112:115], v[128:131], v[88:91], v[112:115]
	v_mfma_f32_16x16x32_bf16 v[120:123], v[128:131], v[92:95], v[120:123]
	global_load_lds_dwordx4 v158, s[10:11]
	ds_read_b128 v[128:131], v175 offset:6144
	s_waitcnt lgkmcnt(5)
	v_mfma_f32_16x16x32_bf16 v[112:115], v[136:139], v[80:83], v[112:115]
	v_mfma_f32_16x16x32_bf16 v[120:123], v[136:139], v[84:87], v[120:123]
	ds_read_b128 v[136:139], v177 offset:6144
	s_waitcnt lgkmcnt(5)
	v_mfma_f32_16x16x32_bf16 v[112:115], v[132:135], v[72:75], v[112:115]
	v_mfma_f32_16x16x32_bf16 v[120:123], v[132:135], v[76:79], v[120:123]
	ds_read_b128 v[132:135], v179 offset:6144
	s_add_i32 m0, s30, 0x2000
	s_waitcnt lgkmcnt(5)
	v_mfma_f32_16x16x32_bf16 v[112:115], v[140:143], v[64:67], v[112:115]
	v_mfma_f32_16x16x32_bf16 v[120:123], v[140:143], v[68:71], v[120:123]
	global_load_lds_dwordx4 v172, s[10:11]
	ds_read_b128 v[140:143], v195 offset:6144
	s_waitcnt lgkmcnt(5)
	v_mfma_f32_16x16x32_bf16 v[116:119], v[204:207], v[104:107], 0
	v_mfma_f32_16x16x32_bf16 v[124:127], v[204:207], v[108:111], 0
	ds_read_b128 v[204:207], v159 offset:12288
	s_waitcnt lgkmcnt(5)
	v_mfma_f32_16x16x32_bf16 v[116:119], v[208:211], v[96:99], v[116:119]
	v_mfma_f32_16x16x32_bf16 v[124:127], v[208:211], v[100:103], v[124:127]
	ds_read_b128 v[208:211], v173 offset:12288
	s_add_i32 m0, s30, 0x4000
	s_waitcnt lgkmcnt(5)
	v_mfma_f32_16x16x32_bf16 v[116:119], v[128:131], v[88:91], v[116:119]
	v_mfma_f32_16x16x32_bf16 v[124:127], v[128:131], v[92:95], v[124:127]
	global_load_lds_dwordx4 v174, s[10:11]
	ds_read_b128 v[234:237], v175 offset:12288
	s_waitcnt lgkmcnt(5)
	v_mfma_f32_16x16x32_bf16 v[116:119], v[136:139], v[80:83], v[116:119]
	v_mfma_f32_16x16x32_bf16 v[124:127], v[136:139], v[84:87], v[124:127]
	ds_read_b128 v[238:241], v177 offset:12288
	s_waitcnt lgkmcnt(5)
	v_mfma_f32_16x16x32_bf16 v[116:119], v[132:135], v[72:75], v[116:119]
	v_mfma_f32_16x16x32_bf16 v[124:127], v[132:135], v[76:79], v[124:127]
	ds_read_b128 v[132:135], v179 offset:12288
	s_add_i32 m0, s30, 0x6000
	s_waitcnt lgkmcnt(5)
	v_mfma_f32_16x16x32_bf16 v[116:119], v[140:143], v[64:67], v[116:119]
	v_mfma_f32_16x16x32_bf16 v[124:127], v[140:143], v[68:71], v[124:127]
	global_load_lds_dwordx4 v176, vcc
	ds_read_b128 v[140:143], v195 offset:12288
	s_waitcnt lgkmcnt(5)
	v_mfma_f32_16x16x32_bf16 v[136:139], v[204:207], v[104:107], 0
	v_mfma_f32_16x16x32_bf16 v[128:131], v[204:207], v[108:111], 0
	ds_read_b128 v[204:207], v159 offset:18432
	s_waitcnt lgkmcnt(5)
	v_mfma_f32_16x16x32_bf16 v[136:139], v[208:211], v[96:99], v[136:139]
	v_mfma_f32_16x16x32_bf16 v[128:131], v[208:211], v[100:103], v[128:131]
	ds_read_b128 v[208:211], v173 offset:18432
	s_add_i32 m0, s30, 0x8000
	s_waitcnt lgkmcnt(5)
	v_mfma_f32_16x16x32_bf16 v[136:139], v[234:237], v[88:91], v[136:139]
	v_mfma_f32_16x16x32_bf16 v[128:131], v[234:237], v[92:95], v[128:131]
	global_load_lds_dwordx4 v178, vcc
	ds_read_b128 v[234:237], v175 offset:18432
	s_waitcnt lgkmcnt(5)
	v_mfma_f32_16x16x32_bf16 v[136:139], v[238:241], v[80:83], v[136:139]
	v_mfma_f32_16x16x32_bf16 v[128:131], v[238:241], v[84:87], v[128:131]
	ds_read_b128 v[238:241], v177 offset:18432
	s_waitcnt lgkmcnt(5)
	v_mfma_f32_16x16x32_bf16 v[136:139], v[132:135], v[72:75], v[136:139]
	v_mfma_f32_16x16x32_bf16 v[128:131], v[132:135], v[76:79], v[128:131]
	ds_read_b128 v[242:245], v179 offset:18432
	s_waitcnt lgkmcnt(5)
	v_mfma_f32_16x16x32_bf16 v[136:139], v[140:143], v[64:67], v[136:139]
	v_mfma_f32_16x16x32_bf16 v[128:131], v[140:143], v[68:71], v[128:131]
	s_cmp_lg_u64 s[6:7], 0
	s_cbranch_scc0 .Lat_v2skip
	s_add_i32 m0, s30, 0xa000
	s_nop 0
	global_load_lds_dwordx4 v160, vcc
.Lat_v2skip:
	ds_read_b128 v[246:249], v195 offset:18432
	s_waitcnt lgkmcnt(5)
	v_mfma_f32_16x16x32_bf16 v[140:143], v[204:207], v[104:107], 0
	v_mfma_f32_16x16x32_bf16 v[132:135], v[204:207], v[108:111], 0
	s_waitcnt lgkmcnt(4)
	v_mfma_f32_16x16x32_bf16 v[140:143], v[208:211], v[96:99], v[140:143]
	v_mfma_f32_16x16x32_bf16 v[132:135], v[208:211], v[100:103], v[132:135]
	s_waitcnt lgkmcnt(3)
	v_mfma_f32_16x16x32_bf16 v[140:143], v[234:237], v[88:91], v[140:143]
	v_mfma_f32_16x16x32_bf16 v[132:135], v[234:237], v[92:95], v[132:135]
	s_waitcnt lgkmcnt(2)
	v_mfma_f32_16x16x32_bf16 v[140:143], v[238:241], v[80:83], v[140:143]
	v_mfma_f32_16x16x32_bf16 v[132:135], v[238:241], v[84:87], v[132:135]
	s_waitcnt lgkmcnt(1)
	v_mfma_f32_16x16x32_bf16 v[140:143], v[242:245], v[72:75], v[140:143]
	v_mfma_f32_16x16x32_bf16 v[132:135], v[242:245], v[76:79], v[132:135]
	s_waitcnt lgkmcnt(0)
	v_mfma_f32_16x16x32_bf16 v[140:143], v[246:249], v[64:67], v[140:143]
	v_mfma_f32_16x16x32_bf16 v[132:135], v[246:249], v[68:71], v[132:135]
	s_cmp_eq_u32 s29, 0
	s_cbranch_scc1 .Lattn_slow_sm
	v_fmamk_f32 v112, v112, 0x3dd53b94, v157
	v_fmamk_f32 v113, v113, 0x3dd53b94, v157
	v_fmamk_f32 v114, v114, 0x3dd53b94, v157
	v_exp_f32_e32 v112, v112
	v_fmamk_f32 v115, v115, 0x3dd53b94, v157
	v_exp_f32_e32 v113, v113
	v_fmamk_f32 v116, v116, 0x3dd53b94, v157
	v_exp_f32_e32 v114, v114
	v_fmamk_f32 v117, v117, 0x3dd53b94, v157
	v_exp_f32_e32 v115, v115
	v_fmamk_f32 v118, v118, 0x3dd53b94, v157
	v_exp_f32_e32 v116, v116
	v_fmamk_f32 v119, v119, 0x3dd53b94, v157
	v_exp_f32_e32 v117, v117
	v_fmamk_f32 v136, v136, 0x3dd53b94, v157
	v_exp_f32_e32 v118, v118
	v_fmamk_f32 v137, v137, 0x3dd53b94, v157
	v_exp_f32_e32 v119, v119
	v_fmamk_f32 v138, v138, 0x3dd53b94, v157
	v_exp_f32_e32 v136, v136
	v_fmamk_f32 v139, v139, 0x3dd53b94, v157
	v_exp_f32_e32 v137, v137
	v_fmamk_f32 v140, v140, 0x3dd53b94, v157
	v_exp_f32_e32 v138, v138
	v_fmamk_f32 v141, v141, 0x3dd53b94, v157
	v_exp_f32_e32 v139, v139
	v_fmamk_f32 v142, v142, 0x3dd53b94, v157
	v_exp_f32_e32 v140, v140
	v_fmamk_f32 v143, v143, 0x3dd53b94, v157
	v_exp_f32_e32 v141, v141
	v_exp_f32_e32 v142, v142
	v_exp_f32_e32 v143, v143
	s_nop 0
	v_add_f32_e32 v204, v112, v113
	v_add_f32_e32 v205, v114, v115
	v_add_f32_e32 v206, v116, v117
	v_add_f32_e32 v207, v118, v119
	v_add_f32_e32 v208, v136, v137
	v_add_f32_e32 v209, v138, v139
	v_add_f32_e32 v210, v140, v141
	v_add_f32_e32 v211, v142, v143
	v_add_f32_e32 v204, v204, v205
	v_add_f32_e32 v206, v206, v207
	v_add_f32_e32 v208, v208, v209
	v_add_f32_e32 v210, v210, v211
	v_add_f32_e32 v204, v204, v206
	v_add_f32_e32 v208, v208, v210
	v_add_f32_e32 v195, v204, v208
	v_fmamk_f32 v120, v120, 0x3dd53b94, v155
	v_fmamk_f32 v121, v121, 0x3dd53b94, v155
	v_fmamk_f32 v122, v122, 0x3dd53b94, v155
	v_exp_f32_e32 v120, v120
	v_fmamk_f32 v123, v123, 0x3dd53b94, v155
	v_exp_f32_e32 v121, v121
	v_fmamk_f32 v124, v124, 0x3dd53b94, v155
	v_exp_f32_e32 v122, v122
	v_fmamk_f32 v125, v125, 0x3dd53b94, v155
	v_exp_f32_e32 v123, v123
	v_fmamk_f32 v126, v126, 0x3dd53b94, v155
	v_exp_f32_e32 v124, v124
	v_fmamk_f32 v127, v127, 0x3dd53b94, v155
	v_exp_f32_e32 v125, v125
	v_fmamk_f32 v128, v128, 0x3dd53b94, v155
	v_exp_f32_e32 v126, v126
	v_fmamk_f32 v129, v129, 0x3dd53b94, v155
	v_exp_f32_e32 v127, v127
	v_fmamk_f32 v130, v130, 0x3dd53b94, v155
	v_exp_f32_e32 v128, v128
	v_fmamk_f32 v131, v131, 0x3dd53b94, v155
	v_exp_f32_e32 v129, v129
	v_fmamk_f32 v132, v132, 0x3dd53b94, v155
	v_exp_f32_e32 v130, v130
	v_fmamk_f32 v133, v133, 0x3dd53b94, v155
	v_exp_f32_e32 v131, v131
	v_fmamk_f32 v134, v134, 0x3dd53b94, v155
	v_exp_f32_e32 v132, v132
	v_fmamk_f32 v135, v135, 0x3dd53b94, v155
	v_exp_f32_e32 v133, v133
	v_exp_f32_e32 v134, v134
	v_exp_f32_e32 v135, v135
	s_nop 0
	v_add_f32_e32 v204, v120, v121
	v_add_f32_e32 v205, v122, v123
	v_add_f32_e32 v206, v124, v125
	v_add_f32_e32 v207, v126, v127
	v_add_f32_e32 v208, v128, v129
	v_add_f32_e32 v209, v130, v131
	v_add_f32_e32 v210, v132, v133
	v_add_f32_e32 v211, v134, v135
	v_add_f32_e32 v204, v204, v205
	v_add_f32_e32 v206, v206, v207
	v_add_f32_e32 v208, v208, v209
	v_add_f32_e32 v210, v210, v211
	v_add_f32_e32 v204, v204, v206
	v_add_f32_e32 v208, v208, v210
	v_add_f32_e32 v230, v204, v208
	v_add_f32_e32 v211, v195, v230
	v_cmp_ge_f32_e32 vcc, 0x47800000, v211
	s_cmp_eq_u64 vcc, exec
	s_cbranch_scc0 .Lattn_slow
	v_add_f32_e32 v156, v156, v195
	v_add_f32_e32 v154, v154, v230
	v_cvt_pk_bf16_f32 v119, v118, v119
	v_cvt_pk_bf16_f32 v118, v116, v117
	v_cvt_pk_bf16_f32 v116, v112, v113
	v_cvt_pk_bf16_f32 v117, v114, v115
	v_cvt_pk_bf16_f32 v112, v136, v137
	v_cvt_pk_bf16_f32 v113, v138, v139
	v_cvt_pk_bf16_f32 v114, v140, v141
	v_cvt_pk_bf16_f32 v115, v142, v143
	v_cvt_pk_bf16_f32 v127, v126, v127
	v_cvt_pk_bf16_f32 v126, v124, v125
	v_cvt_pk_bf16_f32 v124, v120, v121
	v_cvt_pk_bf16_f32 v125, v122, v123
	v_cvt_pk_bf16_f32 v120, v128, v129
	v_cvt_pk_bf16_f32 v121, v130, v131
	v_cvt_pk_bf16_f32 v122, v132, v133
	v_cvt_pk_bf16_f32 v123, v134, v135

.Lattn_slow:
	v_add_u32_e32 v159, s8, v198
	v_add_u32_e32 v173, s8, v199
	v_add_u32_e32 v175, s8, v200
	v_add_u32_e32 v177, s8, v201
	v_add_u32_e32 v179, s8, v225
	v_add_u32_e32 v195, s8, v226
	ds_read_b128 v[116:119], v159
	ds_read_b128 v[124:127], v173
	ds_read_b128 v[128:131], v175
	ds_read_b128 v[136:139], v177
	ds_read_b128 v[132:135], v179
	ds_read_b128 v[140:143], v195
	s_waitcnt lgkmcnt(5)
	v_mfma_f32_16x16x32_bf16 v[112:115], v[116:119], v[104:107], 0
	v_mfma_f32_16x16x32_bf16 v[120:123], v[116:119], v[108:111], 0
	ds_read_b128 v[204:207], v159 offset:6144
	s_waitcnt lgkmcnt(5)
	v_mfma_f32_16x16x32_bf16 v[112:115], v[124:127], v[96:99], v[112:115]
	v_mfma_f32_16x16x32_bf16 v[120:123], v[124:127], v[100:103], v[120:123]
	ds_read_b128 v[208:211], v173 offset:6144
	s_waitcnt lgkmcnt(5)
	v_mfma_f32_16x16x32_bf16 v[112:115], v[128:131], v[88:91], v[112:115]
	v_mfma_f32_16x16x32_bf16 v[120:123], v[128:131], v[92:95], v[120:123]
	ds_read_b128 v[128:131], v175 offset:6144
	s_waitcnt lgkmcnt(5)
	v_mfma_f32_16x16x32_bf16 v[112:115], v[136:139], v[80:83], v[112:115]
	v_mfma_f32_16x16x32_bf16 v[120:123], v[136:139], v[84:87], v[120:123]
	ds_read_b128 v[136:139], v177 offset:6144
	s_waitcnt lgkmcnt(5)
	v_mfma_f32_16x16x32_bf16 v[112:115], v[132:135], v[72:75], v[112:115]
	v_mfma_f32_16x16x32_bf16 v[120:123], v[132:135], v[76:79], v[120:123]
	ds_read_b128 v[132:135], v179 offset:6144
	s_waitcnt lgkmcnt(5)
	v_mfma_f32_16x16x32_bf16 v[112:115], v[140:143], v[64:67], v[112:115]
	v_mfma_f32_16x16x32_bf16 v[120:123], v[140:143], v[68:71], v[120:123]
	ds_read_b128 v[140:143], v195 offset:6144
	s_waitcnt lgkmcnt(5)
	v_mfma_f32_16x16x32_bf16 v[116:119], v[204:207], v[104:107], 0
	v_mfma_f32_16x16x32_bf16 v[124:127], v[204:207], v[108:111], 0
	ds_read_b128 v[204:207], v159 offset:12288
	s_waitcnt lgkmcnt(5)
	v_mfma_f32_16x16x32_bf16 v[116:119], v[208:211], v[96:99], v[116:119]
	v_mfma_f32_16x16x32_bf16 v[124:127], v[208:211], v[100:103], v[124:127]
	ds_read_b128 v[208:211], v173 offset:12288
	s_waitcnt lgkmcnt(5)
	v_mfma_f32_16x16x32_bf16 v[116:119], v[128:131], v[88:91], v[116:119]
	v_mfma_f32_16x16x32_bf16 v[124:127], v[128:131], v[92:95], v[124:127]
	ds_read_b128 v[234:237], v175 offset:12288
	s_waitcnt lgkmcnt(5)
	v_mfma_f32_16x16x32_bf16 v[116:119], v[136:139], v[80:83], v[116:119]
	v_mfma_f32_16x16x32_bf16 v[124:127], v[136:139], v[84:87], v[124:127]
	ds_read_b128 v[238:241], v177 offset:12288
	s_waitcnt lgkmcnt(5)
	v_mfma_f32_16x16x32_bf16 v[116:119], v[132:135], v[72:75], v[116:119]
	v_mfma_f32_16x16x32_bf16 v[124:127], v[132:135], v[76:79], v[124:127]
	ds_read_b128 v[132:135], v179 offset:12288
	s_waitcnt lgkmcnt(5)
	v_mfma_f32_16x16x32_bf16 v[116:119], v[140:143], v[64:67], v[116:119]
	v_mfma_f32_16x16x32_bf16 v[124:127], v[140:143], v[68:71], v[124:127]
	ds_read_b128 v[140:143], v195 offset:12288
	s_waitcnt lgkmcnt(5)
	v_mfma_f32_16x16x32_bf16 v[136:139], v[204:207], v[104:107], 0
	v_mfma_f32_16x16x32_bf16 v[128:131], v[204:207], v[108:111], 0
	ds_read_b128 v[204:207], v159 offset:18432
	s_waitcnt lgkmcnt(5)
	v_mfma_f32_16x16x32_bf16 v[136:139], v[208:211], v[96:99], v[136:139]
	v_mfma_f32_16x16x32_bf16 v[128:131], v[208:211], v[100:103], v[128:131]
	ds_read_b128 v[208:211], v173 offset:18432
	s_waitcnt lgkmcnt(5)
	v_mfma_f32_16x16x32_bf16 v[136:139], v[234:237], v[88:91], v[136:139]
	v_mfma_f32_16x16x32_bf16 v[128:131], v[234:237], v[92:95], v[128:131]
	ds_read_b128 v[234:237], v175 offset:18432
	s_waitcnt lgkmcnt(5)
	v_mfma_f32_16x16x32_bf16 v[136:139], v[238:241], v[80:83], v[136:139]
	v_mfma_f32_16x16x32_bf16 v[128:131], v[238:241], v[84:87], v[128:131]
	ds_read_b128 v[238:241], v177 offset:18432
	s_waitcnt lgkmcnt(5)
	v_mfma_f32_16x16x32_bf16 v[136:139], v[132:135], v[72:75], v[136:139]
	v_mfma_f32_16x16x32_bf16 v[128:131], v[132:135], v[76:79], v[128:131]
	ds_read_b128 v[242:245], v179 offset:18432
	s_waitcnt lgkmcnt(5)
	v_mfma_f32_16x16x32_bf16 v[136:139], v[140:143], v[64:67], v[136:139]
	v_mfma_f32_16x16x32_bf16 v[128:131], v[140:143], v[68:71], v[128:131]
	ds_read_b128 v[246:249], v195 offset:18432
	s_waitcnt lgkmcnt(5)
	v_mfma_f32_16x16x32_bf16 v[140:143], v[204:207], v[104:107], 0
	v_mfma_f32_16x16x32_bf16 v[132:135], v[204:207], v[108:111], 0
	s_waitcnt lgkmcnt(4)
	v_mfma_f32_16x16x32_bf16 v[140:143], v[208:211], v[96:99], v[140:143]
	v_mfma_f32_16x16x32_bf16 v[132:135], v[208:211], v[100:103], v[132:135]
	s_waitcnt lgkmcnt(3)
	v_mfma_f32_16x16x32_bf16 v[140:143], v[234:237], v[88:91], v[140:143]
	v_mfma_f32_16x16x32_bf16 v[132:135], v[234:237], v[92:95], v[132:135]
	s_waitcnt lgkmcnt(2)
	v_mfma_f32_16x16x32_bf16 v[140:143], v[238:241], v[80:83], v[140:143]
	v_mfma_f32_16x16x32_bf16 v[132:135], v[238:241], v[84:87], v[132:135]
	s_waitcnt lgkmcnt(1)
	v_mfma_f32_16x16x32_bf16 v[140:143], v[242:245], v[72:75], v[140:143]
	v_mfma_f32_16x16x32_bf16 v[132:135], v[242:245], v[76:79], v[132:135]
	s_waitcnt lgkmcnt(0)
	v_mfma_f32_16x16x32_bf16 v[140:143], v[246:249], v[64:67], v[140:143]
	v_mfma_f32_16x16x32_bf16 v[132:135], v[246:249], v[68:71], v[132:135]

.Lattn_exit:
	v_add_u32_e32 v234, 0x1800, v198
	v_add_u32_e32 v235, 0x1800, v199
	v_add_u32_e32 v236, 0x1800, v200
	v_add_u32_e32 v237, 0x1800, v201
	v_add_u32_e32 v238, 0x1800, v225
	v_add_u32_e32 v239, 0x1800, v226
	v_add_u32_e32 v240, 0x3000, v198
	v_add_u32_e32 v241, 0x3000, v199
	v_add_u32_e32 v242, 0x3000, v200
	v_add_u32_e32 v243, 0x3000, v201
	v_add_u32_e32 v244, 0x3000, v225
	v_add_u32_e32 v245, 0x3000, v226
	v_add_u32_e32 v246, 0x4800, v198
	v_add_u32_e32 v247, 0x4800, v199
	v_add_u32_e32 v248, 0x4800, v200
	v_add_u32_e32 v249, 0x4800, v201
	v_add_u32_e32 v250, 0x4800, v225
	v_add_u32_e32 v251, 0x4800, v226
